# G2/G4 epilogue: last 12 of 16 residual stores transposed through the per-wave LDS slot
# baseline (speedup 1.0000x reference)
.LBB0_768:
	s_or_b64 exec, exec, s[0:1]
	v_lshlrev_b32_e32 v96, 16, v172
	s_waitcnt lgkmcnt(0)
	v_and_b32_e32 v97, 0xffff0000, v172
	v_pk_add_f32 v[84:85], v[84:85], v[96:97]
	v_lshlrev_b32_e32 v96, 16, v173
	v_and_b32_e32 v97, 0xffff0000, v173
	v_pk_add_f32 v[86:87], v[86:87], v[96:97]
	v_cvt_pk_bf16_f32 v84, v84, v85
	v_cvt_pk_bf16_f32 v85, v86, v87
	v_lshlrev_b32_e32 v86, 16, v174
	v_and_b32_e32 v87, 0xffff0000, v174
	v_pk_add_f32 v[80:81], v[80:81], v[86:87]
	s_nop 0
	v_cvt_pk_bf16_f32 v86, v80, v81
	v_lshlrev_b32_e32 v80, 16, v175
	v_and_b32_e32 v81, 0xffff0000, v175
	v_pk_add_f32 v[80:81], v[82:83], v[80:81]
	v_lshlrev_b32_e32 v82, 16, v85
	v_cvt_pk_bf16_f32 v87, v80, v81
	v_and_b32_e32 v81, 0xffff0000, v84
	v_lshlrev_b32_e32 v80, 16, v84
	v_mul_f32_e32 v100, v81, v81
	v_fmac_f32_e32 v100, v80, v80
	v_lshlrev_b32_e32 v80, 16, v168
	v_and_b32_e32 v81, 0xffff0000, v168
	v_pk_add_f32 v[80:81], v[92:93], v[80:81]
	v_and_b32_e32 v83, 0xffff0000, v85
	v_cvt_pk_bf16_f32 v92, v80, v81
	v_lshlrev_b32_e32 v80, 16, v169
	v_and_b32_e32 v81, 0xffff0000, v169
	v_fmac_f32_e32 v100, v82, v82
	v_pk_add_f32 v[80:81], v[94:95], v[80:81]
	v_lshlrev_b32_e32 v96, 16, v86
	v_fmac_f32_e32 v100, v83, v83
	v_cvt_pk_bf16_f32 v93, v80, v81
	v_lshlrev_b32_e32 v80, 16, v170
	v_and_b32_e32 v81, 0xffff0000, v170
	v_and_b32_e32 v97, 0xffff0000, v86
	v_fmac_f32_e32 v100, v96, v96
	v_pk_add_f32 v[80:81], v[88:89], v[80:81]
	v_lshlrev_b32_e32 v98, 16, v87
	v_fmac_f32_e32 v100, v97, v97
	v_cvt_pk_bf16_f32 v94, v80, v81
	v_lshlrev_b32_e32 v80, 16, v171
	v_and_b32_e32 v81, 0xffff0000, v171
	v_and_b32_e32 v99, 0xffff0000, v87
	v_fmac_f32_e32 v100, v98, v98
	v_pk_add_f32 v[80:81], v[90:91], v[80:81]
	v_fmac_f32_e32 v100, v99, v99
	v_cvt_pk_bf16_f32 v95, v80, v81
	v_lshlrev_b32_e32 v80, 16, v92
	v_and_b32_e32 v81, 0xffff0000, v92
	v_fmac_f32_e32 v100, v80, v80
	v_lshlrev_b32_e32 v82, 16, v93
	v_fmac_f32_e32 v100, v81, v81
	v_and_b32_e32 v83, 0xffff0000, v93
	v_fmac_f32_e32 v100, v82, v82
	v_lshlrev_b32_e32 v88, 16, v94
	v_fmac_f32_e32 v100, v83, v83
	v_and_b32_e32 v89, 0xffff0000, v94
	v_fmac_f32_e32 v100, v88, v88
	v_lshlrev_b32_e32 v90, 16, v95
	v_fmac_f32_e32 v100, v89, v89
	v_and_b32_e32 v91, 0xffff0000, v95
	v_fmac_f32_e32 v100, v90, v90
	v_fmac_f32_e32 v100, v91, v91
	ds_bpermute_b32 v80, v249, v100
	v_lshl_add_u64 v[82:83], s[12:13], 0, v[228:229]
	v_lshl_add_u64 v[82:83], v[216:217], 1, v[82:83]
	v_mbcnt_lo_u32_b32 v168, -1, 0
	v_mbcnt_hi_u32_b32 v168, -1, v168
	v_and_b32_e32 v169, 15, v168
	v_lshrrev_b32_e32 v170, 4, v168
	v_lshrrev_b32_e32 v182, 2, v169
	v_xor_b32_e32 v182, v182, v170
	v_lshlrev_b32_e32 v182, 4, v182
	v_lshl_or_b32 v182, v169, 6, v182
	s_lshl_b32 s100, s89, 11
	s_add_i32 s100, s100, 0x20000
	v_add_u32_e32 v182, s100, v182
	v_lshl_add_u32 v183, v168, 4, s100
	v_lshrrev_b32_e32 v180, 2, v168
	v_sub_u32_e32 v180, v180, v169
	v_mul_i32_i24_e32 v180, 0x800, v180
	v_and_b32_e32 v181, 3, v168
	v_xor_b32_e32 v181, v181, v170
	v_sub_u32_e32 v181, v181, v170
	v_lshlrev_b32_e32 v181, 4, v181
	v_add_u32_e32 v180, v180, v181
	v_ashrrev_i32_e32 v181, 31, v180
	ds_write_b128 v182, v[84:87]
	ds_read_b128 v[168:171], v183
	v_lshl_add_u64 v[176:177], v[82:83], 0, v[180:181]
	ds_write_b128 v182, v[92:95] offset:1024
	ds_read_b128 v[172:175], v183 offset:1024
	v_lshl_add_u64 v[178:179], v[82:83], 0, v[180:181]
	s_waitcnt lgkmcnt(2)
	global_store_dwordx4 v[176:177], v[168:171], off
	s_waitcnt lgkmcnt(0)
	v_add_f32_e32 v80, v100, v80
	ds_bpermute_b32 v81, v250, v80
	s_and_saveexec_b64 s[0:1], s[8:9]
	s_cbranch_execz .LBB0_770
	s_waitcnt lgkmcnt(0)
	v_add_f32_e32 v80, v80, v81
	v_fma_f32 v80, v80, s6, 0.5
	v_trunc_f32_e32 v80, v80
	v_mul_f32_e32 v81, 0x2f800000, v80
	v_floor_f32_e32 v81, v81
	v_fmac_f32_e32 v80, 0xcf800000, v81
	v_cvt_u32_f32_e32 v80, v80
	v_cvt_u32_f32_e32 v81, v81
	global_atomic_add_x2 v[112:113], v[80:81], off offset:256
.LBB0_770:
	s_or_b64 exec, exec, s[0:1]
	v_lshlrev_b32_e32 v80, 16, v164
	s_waitcnt lgkmcnt(0)
	v_and_b32_e32 v81, 0xffff0000, v164
	v_pk_add_f32 v[68:69], v[68:69], v[80:81]
	v_lshlrev_b32_e32 v80, 16, v165
	v_and_b32_e32 v81, 0xffff0000, v165
	v_pk_add_f32 v[70:71], v[70:71], v[80:81]
	v_cvt_pk_bf16_f32 v68, v68, v69
	v_cvt_pk_bf16_f32 v69, v70, v71
	v_lshlrev_b32_e32 v70, 16, v166
	v_and_b32_e32 v71, 0xffff0000, v166
	v_pk_add_f32 v[60:61], v[60:61], v[70:71]
	s_nop 0
	v_cvt_pk_bf16_f32 v70, v60, v61
	v_lshlrev_b32_e32 v60, 16, v167
	v_and_b32_e32 v61, 0xffff0000, v167
	v_pk_add_f32 v[60:61], v[62:63], v[60:61]
	v_lshlrev_b32_e32 v62, 16, v69
	v_cvt_pk_bf16_f32 v71, v60, v61
	v_and_b32_e32 v61, 0xffff0000, v68
	v_lshlrev_b32_e32 v60, 16, v68
	v_mul_f32_e32 v84, v61, v61
	v_fmac_f32_e32 v84, v60, v60
	v_lshlrev_b32_e32 v60, 16, v160
	v_and_b32_e32 v61, 0xffff0000, v160
	v_pk_add_f32 v[60:61], v[76:77], v[60:61]
	v_and_b32_e32 v63, 0xffff0000, v69
	v_cvt_pk_bf16_f32 v76, v60, v61
	v_lshlrev_b32_e32 v60, 16, v161
	v_and_b32_e32 v61, 0xffff0000, v161
	v_fmac_f32_e32 v84, v62, v62
	v_pk_add_f32 v[60:61], v[78:79], v[60:61]
	v_lshlrev_b32_e32 v80, 16, v70
	v_fmac_f32_e32 v84, v63, v63
	v_cvt_pk_bf16_f32 v77, v60, v61
	v_lshlrev_b32_e32 v60, 16, v162
	v_and_b32_e32 v61, 0xffff0000, v162
	v_and_b32_e32 v81, 0xffff0000, v70
	v_fmac_f32_e32 v84, v80, v80
	v_pk_add_f32 v[60:61], v[72:73], v[60:61]
	v_lshlrev_b32_e32 v82, 16, v71
	v_fmac_f32_e32 v84, v81, v81
	v_cvt_pk_bf16_f32 v78, v60, v61
	v_lshlrev_b32_e32 v60, 16, v163
	v_and_b32_e32 v61, 0xffff0000, v163
	v_and_b32_e32 v83, 0xffff0000, v71
	v_fmac_f32_e32 v84, v82, v82
	v_pk_add_f32 v[60:61], v[74:75], v[60:61]
	v_fmac_f32_e32 v84, v83, v83
	v_cvt_pk_bf16_f32 v79, v60, v61
	v_lshlrev_b32_e32 v60, 16, v76
	v_and_b32_e32 v61, 0xffff0000, v76
	v_fmac_f32_e32 v84, v60, v60
	v_lshlrev_b32_e32 v62, 16, v77
	v_fmac_f32_e32 v84, v61, v61
	v_and_b32_e32 v63, 0xffff0000, v77
	v_fmac_f32_e32 v84, v62, v62
	v_lshlrev_b32_e32 v72, 16, v78
	v_fmac_f32_e32 v84, v63, v63
	v_and_b32_e32 v73, 0xffff0000, v78
	v_fmac_f32_e32 v84, v72, v72
	v_lshlrev_b32_e32 v74, 16, v79
	v_fmac_f32_e32 v84, v73, v73
	v_and_b32_e32 v75, 0xffff0000, v79
	v_fmac_f32_e32 v84, v74, v74
	v_fmac_f32_e32 v84, v75, v75
	ds_bpermute_b32 v60, v249, v84
	v_lshl_add_u64 v[62:63], s[12:13], 0, v[226:227]
	v_lshl_add_u64 v[62:63], v[216:217], 1, v[62:63]
	ds_write_b128 v182, v[68:71]
	ds_read_b128 v[168:171], v183
	v_lshl_add_u64 v[176:177], v[62:63], 0, v[180:181]
	s_waitcnt lgkmcnt(2)
	global_store_dwordx4 v[178:179], v[172:175], off offset:256
	ds_write_b128 v182, v[76:79] offset:1024
	ds_read_b128 v[172:175], v183 offset:1024
	v_lshl_add_u64 v[178:179], v[62:63], 0, v[180:181]
	s_waitcnt lgkmcnt(2)
	global_store_dwordx4 v[176:177], v[168:171], off
	s_waitcnt lgkmcnt(0)
	v_add_f32_e32 v60, v84, v60
	ds_bpermute_b32 v61, v250, v60
	s_and_saveexec_b64 s[0:1], s[8:9]
	s_cbranch_execz .LBB0_772
	s_waitcnt lgkmcnt(0)
	v_add_f32_e32 v60, v60, v61
	v_fma_f32 v60, v60, s6, 0.5
	v_trunc_f32_e32 v60, v60
	v_mul_f32_e32 v61, 0x2f800000, v60
	v_floor_f32_e32 v61, v61
	v_fmac_f32_e32 v60, 0xcf800000, v61
	v_cvt_u32_f32_e32 v60, v60
	v_cvt_u32_f32_e32 v61, v61
	global_atomic_add_x2 v[112:113], v[60:61], off offset:384
.LBB0_772:
	s_or_b64 exec, exec, s[0:1]
	v_lshlrev_b32_e32 v60, 16, v156
	s_waitcnt lgkmcnt(0)
	v_and_b32_e32 v61, 0xffff0000, v156
	v_pk_add_f32 v[52:53], v[52:53], v[60:61]
	v_lshlrev_b32_e32 v60, 16, v157
	v_and_b32_e32 v61, 0xffff0000, v157
	v_pk_add_f32 v[54:55], v[54:55], v[60:61]
	v_cvt_pk_bf16_f32 v52, v52, v53
	v_cvt_pk_bf16_f32 v53, v54, v55
	v_lshlrev_b32_e32 v54, 16, v158
	v_and_b32_e32 v55, 0xffff0000, v158
	v_pk_add_f32 v[48:49], v[48:49], v[54:55]
	s_nop 0
	v_cvt_pk_bf16_f32 v54, v48, v49
	v_lshlrev_b32_e32 v48, 16, v159
	v_and_b32_e32 v49, 0xffff0000, v159
	v_pk_add_f32 v[48:49], v[50:51], v[48:49]
	v_lshlrev_b32_e32 v50, 16, v53
	v_cvt_pk_bf16_f32 v55, v48, v49
	v_and_b32_e32 v49, 0xffff0000, v52
	v_lshlrev_b32_e32 v48, 16, v52
	v_mul_f32_e32 v68, v49, v49
	v_fmac_f32_e32 v68, v48, v48
	v_and_b32_e32 v51, 0xffff0000, v53
	v_fmac_f32_e32 v68, v50, v50
	v_lshlrev_b32_e32 v48, 16, v152
	v_and_b32_e32 v49, 0xffff0000, v152
	v_lshlrev_b32_e32 v60, 16, v54
	v_fmac_f32_e32 v68, v51, v51
	v_pk_add_f32 v[48:49], v[64:65], v[48:49]
	v_fmac_f32_e32 v68, v60, v60
	v_cvt_pk_bf16_f32 v60, v48, v49
	v_lshlrev_b32_e32 v48, 16, v153
	v_and_b32_e32 v49, 0xffff0000, v153
	v_and_b32_e32 v61, 0xffff0000, v54
	v_pk_add_f32 v[48:49], v[66:67], v[48:49]
	v_fmac_f32_e32 v68, v61, v61
	v_cvt_pk_bf16_f32 v61, v48, v49
	v_lshlrev_b32_e32 v48, 16, v154
	v_and_b32_e32 v49, 0xffff0000, v154
	v_lshlrev_b32_e32 v62, 16, v55
	v_pk_add_f32 v[48:49], v[56:57], v[48:49]
	v_fmac_f32_e32 v68, v62, v62
	v_cvt_pk_bf16_f32 v62, v48, v49
	v_lshlrev_b32_e32 v48, 16, v155
	v_and_b32_e32 v49, 0xffff0000, v155
	v_and_b32_e32 v63, 0xffff0000, v55
	v_pk_add_f32 v[48:49], v[58:59], v[48:49]
	v_fmac_f32_e32 v68, v63, v63
	v_cvt_pk_bf16_f32 v63, v48, v49
	v_lshlrev_b32_e32 v48, 16, v60
	v_and_b32_e32 v49, 0xffff0000, v60
	v_fmac_f32_e32 v68, v48, v48
	v_lshlrev_b32_e32 v50, 16, v61
	v_fmac_f32_e32 v68, v49, v49
	v_and_b32_e32 v51, 0xffff0000, v61
	v_fmac_f32_e32 v68, v50, v50
	v_lshlrev_b32_e32 v56, 16, v62
	v_fmac_f32_e32 v68, v51, v51
	v_and_b32_e32 v57, 0xffff0000, v62
	v_fmac_f32_e32 v68, v56, v56
	v_lshlrev_b32_e32 v58, 16, v63
	v_fmac_f32_e32 v68, v57, v57
	v_and_b32_e32 v59, 0xffff0000, v63
	v_fmac_f32_e32 v68, v58, v58
	v_fmac_f32_e32 v68, v59, v59
	ds_bpermute_b32 v48, v249, v68
	v_lshl_add_u64 v[50:51], s[12:13], 0, v[224:225]
	v_lshl_add_u64 v[50:51], v[216:217], 1, v[50:51]
	ds_write_b128 v182, v[52:55]
	ds_read_b128 v[168:171], v183
	v_lshl_add_u64 v[176:177], v[50:51], 0, v[180:181]
	s_waitcnt lgkmcnt(2)
	global_store_dwordx4 v[178:179], v[172:175], off offset:256
	ds_write_b128 v182, v[60:63] offset:1024
	ds_read_b128 v[172:175], v183 offset:1024
	v_lshl_add_u64 v[178:179], v[50:51], 0, v[180:181]
	s_waitcnt lgkmcnt(2)
	global_store_dwordx4 v[176:177], v[168:171], off
	s_waitcnt lgkmcnt(0)
	v_add_f32_e32 v48, v68, v48
	ds_bpermute_b32 v49, v250, v48
	s_and_saveexec_b64 s[0:1], s[8:9]
	s_cbranch_execz .LBB0_774
	s_waitcnt lgkmcnt(0)
	v_add_f32_e32 v48, v48, v49
	v_fma_f32 v48, v48, s6, 0.5
	v_trunc_f32_e32 v48, v48
	v_mul_f32_e32 v49, 0x2f800000, v48
	v_floor_f32_e32 v49, v49
	v_fmac_f32_e32 v48, 0xcf800000, v49
	v_cvt_u32_f32_e32 v48, v48
	v_cvt_u32_f32_e32 v49, v49
	global_atomic_add_x2 v[112:113], v[48:49], off offset:1024
.LBB0_774:
	s_or_b64 exec, exec, s[0:1]
	v_lshlrev_b32_e32 v48, 16, v148
	s_waitcnt lgkmcnt(0)
	v_and_b32_e32 v49, 0xffff0000, v148
	v_pk_add_f32 v[36:37], v[36:37], v[48:49]
	v_lshlrev_b32_e32 v48, 16, v149
	v_and_b32_e32 v49, 0xffff0000, v149
	v_pk_add_f32 v[38:39], v[38:39], v[48:49]
	v_cvt_pk_bf16_f32 v36, v36, v37
	v_cvt_pk_bf16_f32 v37, v38, v39
	v_lshlrev_b32_e32 v38, 16, v150
	v_and_b32_e32 v39, 0xffff0000, v150
	v_pk_add_f32 v[32:33], v[32:33], v[38:39]
	s_nop 0
	v_cvt_pk_bf16_f32 v38, v32, v33
	v_lshlrev_b32_e32 v32, 16, v151
	v_and_b32_e32 v33, 0xffff0000, v151
	v_pk_add_f32 v[32:33], v[34:35], v[32:33]
	v_lshlrev_b32_e32 v34, 16, v37
	v_cvt_pk_bf16_f32 v39, v32, v33
	v_and_b32_e32 v33, 0xffff0000, v36
	v_lshlrev_b32_e32 v32, 16, v36
	v_mul_f32_e32 v52, v33, v33
	v_fmac_f32_e32 v52, v32, v32
	v_lshlrev_b32_e32 v32, 16, v144
	v_and_b32_e32 v33, 0xffff0000, v144
	v_pk_add_f32 v[32:33], v[44:45], v[32:33]
	v_and_b32_e32 v35, 0xffff0000, v37
	v_cvt_pk_bf16_f32 v44, v32, v33
	v_lshlrev_b32_e32 v32, 16, v145
	v_and_b32_e32 v33, 0xffff0000, v145
	v_fmac_f32_e32 v52, v34, v34
	v_pk_add_f32 v[32:33], v[46:47], v[32:33]
	v_lshlrev_b32_e32 v48, 16, v38
	v_fmac_f32_e32 v52, v35, v35
	v_cvt_pk_bf16_f32 v45, v32, v33
	v_lshlrev_b32_e32 v32, 16, v146
	v_and_b32_e32 v33, 0xffff0000, v146
	v_and_b32_e32 v49, 0xffff0000, v38
	v_fmac_f32_e32 v52, v48, v48
	v_pk_add_f32 v[32:33], v[40:41], v[32:33]
	v_lshlrev_b32_e32 v50, 16, v39
	v_fmac_f32_e32 v52, v49, v49
	v_cvt_pk_bf16_f32 v46, v32, v33
	v_lshlrev_b32_e32 v32, 16, v147
	v_and_b32_e32 v33, 0xffff0000, v147
	v_and_b32_e32 v51, 0xffff0000, v39
	v_fmac_f32_e32 v52, v50, v50
	v_pk_add_f32 v[32:33], v[42:43], v[32:33]
	v_fmac_f32_e32 v52, v51, v51
	v_cvt_pk_bf16_f32 v47, v32, v33
	v_lshlrev_b32_e32 v32, 16, v44
	v_and_b32_e32 v33, 0xffff0000, v44
	v_fmac_f32_e32 v52, v32, v32
	v_lshlrev_b32_e32 v34, 16, v45
	v_fmac_f32_e32 v52, v33, v33
	v_and_b32_e32 v35, 0xffff0000, v45
	v_fmac_f32_e32 v52, v34, v34
	v_lshlrev_b32_e32 v40, 16, v46
	v_fmac_f32_e32 v52, v35, v35
	v_and_b32_e32 v41, 0xffff0000, v46
	v_fmac_f32_e32 v52, v40, v40
	v_lshlrev_b32_e32 v42, 16, v47
	v_fmac_f32_e32 v52, v41, v41
	v_and_b32_e32 v43, 0xffff0000, v47
	v_fmac_f32_e32 v52, v42, v42
	v_fmac_f32_e32 v52, v43, v43
	ds_bpermute_b32 v32, v249, v52
	v_lshl_add_u64 v[34:35], s[12:13], 0, v[222:223]
	v_lshl_add_u64 v[34:35], v[216:217], 1, v[34:35]
	ds_write_b128 v182, v[36:39]
	ds_read_b128 v[168:171], v183
	v_lshl_add_u64 v[176:177], v[34:35], 0, v[180:181]
	s_waitcnt lgkmcnt(2)
	global_store_dwordx4 v[178:179], v[172:175], off offset:256
	ds_write_b128 v182, v[44:47] offset:1024
	ds_read_b128 v[172:175], v183 offset:1024
	v_lshl_add_u64 v[178:179], v[34:35], 0, v[180:181]
	s_waitcnt lgkmcnt(2)
	global_store_dwordx4 v[176:177], v[168:171], off
	s_waitcnt lgkmcnt(0)
	v_add_f32_e32 v32, v52, v32
	ds_bpermute_b32 v33, v250, v32
	s_and_saveexec_b64 s[0:1], s[8:9]
	s_cbranch_execz .LBB0_776
	s_waitcnt lgkmcnt(0)
	v_add_f32_e32 v32, v32, v33
	v_fma_f32 v32, v32, s6, 0.5
	v_trunc_f32_e32 v32, v32
	v_mul_f32_e32 v33, 0x2f800000, v32
	v_floor_f32_e32 v33, v33
	v_fmac_f32_e32 v32, 0xcf800000, v33
	v_cvt_u32_f32_e32 v32, v32
	v_cvt_u32_f32_e32 v33, v33
	global_atomic_add_x2 v[112:113], v[32:33], off offset:1152
.LBB0_776:
	s_or_b64 exec, exec, s[0:1]
	v_lshlrev_b32_e32 v32, 16, v140
	s_waitcnt lgkmcnt(0)
	v_and_b32_e32 v33, 0xffff0000, v140
	v_pk_add_f32 v[20:21], v[20:21], v[32:33]
	v_lshlrev_b32_e32 v32, 16, v141
	v_and_b32_e32 v33, 0xffff0000, v141
	v_pk_add_f32 v[22:23], v[22:23], v[32:33]
	v_cvt_pk_bf16_f32 v20, v20, v21
	v_cvt_pk_bf16_f32 v21, v22, v23
	v_lshlrev_b32_e32 v22, 16, v142
	v_and_b32_e32 v23, 0xffff0000, v142
	v_pk_add_f32 v[16:17], v[16:17], v[22:23]
	s_nop 0
	v_cvt_pk_bf16_f32 v22, v16, v17
	v_lshlrev_b32_e32 v16, 16, v143
	v_and_b32_e32 v17, 0xffff0000, v143
	v_pk_add_f32 v[16:17], v[18:19], v[16:17]
	v_lshlrev_b32_e32 v18, 16, v21
	v_cvt_pk_bf16_f32 v23, v16, v17
	v_and_b32_e32 v17, 0xffff0000, v20
	v_lshlrev_b32_e32 v16, 16, v20
	v_mul_f32_e32 v36, v17, v17
	v_fmac_f32_e32 v36, v16, v16
	v_lshlrev_b32_e32 v16, 16, v136
	v_and_b32_e32 v17, 0xffff0000, v136
	v_pk_add_f32 v[16:17], v[28:29], v[16:17]
	v_and_b32_e32 v19, 0xffff0000, v21
	v_cvt_pk_bf16_f32 v28, v16, v17
	v_lshlrev_b32_e32 v16, 16, v137
	v_and_b32_e32 v17, 0xffff0000, v137
	v_fmac_f32_e32 v36, v18, v18
	v_pk_add_f32 v[16:17], v[30:31], v[16:17]
	v_lshlrev_b32_e32 v32, 16, v22
	v_fmac_f32_e32 v36, v19, v19
	v_cvt_pk_bf16_f32 v29, v16, v17
	v_lshlrev_b32_e32 v16, 16, v138
	v_and_b32_e32 v17, 0xffff0000, v138
	v_and_b32_e32 v33, 0xffff0000, v22
	v_fmac_f32_e32 v36, v32, v32
	v_pk_add_f32 v[16:17], v[24:25], v[16:17]
	v_lshlrev_b32_e32 v34, 16, v23
	v_fmac_f32_e32 v36, v33, v33
	v_cvt_pk_bf16_f32 v30, v16, v17
	v_lshlrev_b32_e32 v16, 16, v139
	v_and_b32_e32 v17, 0xffff0000, v139
	v_and_b32_e32 v35, 0xffff0000, v23
	v_fmac_f32_e32 v36, v34, v34
	v_pk_add_f32 v[16:17], v[26:27], v[16:17]
	v_fmac_f32_e32 v36, v35, v35
	v_cvt_pk_bf16_f32 v31, v16, v17
	v_lshlrev_b32_e32 v16, 16, v28
	v_and_b32_e32 v17, 0xffff0000, v28
	v_fmac_f32_e32 v36, v16, v16
	v_lshlrev_b32_e32 v18, 16, v29
	v_fmac_f32_e32 v36, v17, v17
	v_and_b32_e32 v19, 0xffff0000, v29
	v_fmac_f32_e32 v36, v18, v18
	v_lshlrev_b32_e32 v24, 16, v30
	v_fmac_f32_e32 v36, v19, v19
	v_and_b32_e32 v25, 0xffff0000, v30
	v_fmac_f32_e32 v36, v24, v24
	v_lshlrev_b32_e32 v26, 16, v31
	v_fmac_f32_e32 v36, v25, v25
	v_and_b32_e32 v27, 0xffff0000, v31
	v_fmac_f32_e32 v36, v26, v26
	v_fmac_f32_e32 v36, v27, v27
	ds_bpermute_b32 v16, v249, v36
	v_lshl_add_u64 v[18:19], s[12:13], 0, v[220:221]
	v_lshl_add_u64 v[18:19], v[216:217], 1, v[18:19]
	ds_write_b128 v182, v[20:23]
	ds_read_b128 v[168:171], v183
	v_lshl_add_u64 v[176:177], v[18:19], 0, v[180:181]
	s_waitcnt lgkmcnt(2)
	global_store_dwordx4 v[178:179], v[172:175], off offset:256
	ds_write_b128 v182, v[28:31] offset:1024
	ds_read_b128 v[172:175], v183 offset:1024
	v_lshl_add_u64 v[178:179], v[18:19], 0, v[180:181]
	s_waitcnt lgkmcnt(2)
	global_store_dwordx4 v[176:177], v[168:171], off
	s_waitcnt lgkmcnt(0)
	v_add_f32_e32 v16, v36, v16
	ds_bpermute_b32 v17, v250, v16
	s_and_saveexec_b64 s[0:1], s[8:9]
	s_cbranch_execz .LBB0_778
	s_waitcnt lgkmcnt(0)
	v_add_f32_e32 v16, v16, v17
	v_fma_f32 v16, v16, s6, 0.5
	v_trunc_f32_e32 v16, v16
	v_mul_f32_e32 v17, 0x2f800000, v16
	v_floor_f32_e32 v17, v17
	v_fmac_f32_e32 v16, 0xcf800000, v17
	v_cvt_u32_f32_e32 v16, v16
	v_cvt_u32_f32_e32 v17, v17
	global_atomic_add_x2 v[112:113], v[16:17], off offset:1280
.LBB0_778:
	s_or_b64 exec, exec, s[0:1]
	v_lshlrev_b32_e32 v18, 16, v132
	v_and_b32_e32 v19, 0xffff0000, v132
	v_pk_add_f32 v[4:5], v[4:5], v[18:19]
	v_lshlrev_b32_e32 v18, 16, v133
	v_and_b32_e32 v19, 0xffff0000, v133
	v_pk_add_f32 v[6:7], v[6:7], v[18:19]
	v_cvt_pk_bf16_f32 v4, v4, v5
	v_cvt_pk_bf16_f32 v5, v6, v7
	v_lshlrev_b32_e32 v6, 16, v134
	v_and_b32_e32 v7, 0xffff0000, v134
	v_pk_add_f32 v[0:1], v[0:1], v[6:7]
	s_waitcnt lgkmcnt(0)
	v_lshl_add_u64 v[16:17], s[12:13], 0, v[218:219]
	v_cvt_pk_bf16_f32 v6, v0, v1
	v_lshlrev_b32_e32 v0, 16, v135
	v_and_b32_e32 v1, 0xffff0000, v135
	v_pk_add_f32 v[0:1], v[2:3], v[0:1]
	v_lshlrev_b32_e32 v2, 16, v5
	v_cvt_pk_bf16_f32 v7, v0, v1
	v_and_b32_e32 v1, 0xffff0000, v4
	v_lshlrev_b32_e32 v0, 16, v4
	v_mul_f32_e32 v18, v1, v1
	v_fmac_f32_e32 v18, v0, v0
	v_lshl_add_u64 v[16:17], v[216:217], 1, v[16:17]
	v_and_b32_e32 v3, 0xffff0000, v5
	v_fmac_f32_e32 v18, v2, v2
	ds_write_b128 v182, v[4:7]
	ds_read_b128 v[168:171], v183
	v_lshl_add_u64 v[176:177], v[16:17], 0, v[180:181]
	s_waitcnt lgkmcnt(2)
	global_store_dwordx4 v[178:179], v[172:175], off offset:256
	v_fmac_f32_e32 v18, v3, v3
	v_lshlrev_b32_e32 v0, 16, v128
	v_lshlrev_b32_e32 v4, 16, v6
	v_and_b32_e32 v1, 0xffff0000, v128
	v_lshlrev_b32_e32 v2, 16, v129
	v_and_b32_e32 v3, 0xffff0000, v129
	v_and_b32_e32 v5, 0xffff0000, v6
	v_fmac_f32_e32 v18, v4, v4
	v_pk_add_f32 v[0:1], v[12:13], v[0:1]
	v_pk_add_f32 v[2:3], v[14:15], v[2:3]
	v_lshlrev_b32_e32 v6, 16, v7
	v_fmac_f32_e32 v18, v5, v5
	v_cvt_pk_bf16_f32 v0, v0, v1
	v_cvt_pk_bf16_f32 v1, v2, v3
	v_lshlrev_b32_e32 v2, 16, v130
	v_and_b32_e32 v3, 0xffff0000, v130
	v_lshlrev_b32_e32 v4, 16, v131
	v_and_b32_e32 v5, 0xffff0000, v131
	v_and_b32_e32 v7, 0xffff0000, v7
	v_fmac_f32_e32 v18, v6, v6
	v_pk_add_f32 v[2:3], v[8:9], v[2:3]
	v_pk_add_f32 v[4:5], v[10:11], v[4:5]
	v_fmac_f32_e32 v18, v7, v7
	v_cvt_pk_bf16_f32 v2, v2, v3
	v_cvt_pk_bf16_f32 v3, v4, v5
	v_lshlrev_b32_e32 v4, 16, v0
	ds_write_b128 v182, v[0:3] offset:1024
	ds_read_b128 v[172:175], v183 offset:1024
	v_lshl_add_u64 v[178:179], v[16:17], 0, v[180:181]
	s_waitcnt lgkmcnt(2)
	global_store_dwordx4 v[176:177], v[168:171], off
	s_waitcnt lgkmcnt(0)
	global_store_dwordx4 v[178:179], v[172:175], off offset:256
	v_fmac_f32_e32 v18, v4, v4
	v_lshlrev_b32_e32 v5, 16, v1
	v_and_b32_e32 v0, 0xffff0000, v0
	v_fmac_f32_e32 v18, v0, v0
	v_and_b32_e32 v1, 0xffff0000, v1
	v_fmac_f32_e32 v18, v5, v5
	v_lshlrev_b32_e32 v6, 16, v2
	v_fmac_f32_e32 v18, v1, v1
	v_and_b32_e32 v2, 0xffff0000, v2
	v_fmac_f32_e32 v18, v6, v6
	v_lshlrev_b32_e32 v7, 16, v3
	v_fmac_f32_e32 v18, v2, v2
	v_and_b32_e32 v3, 0xffff0000, v3
	v_fmac_f32_e32 v18, v7, v7
	v_fmac_f32_e32 v18, v3, v3
	ds_bpermute_b32 v0, v249, v18
	s_waitcnt lgkmcnt(0)
	v_add_f32_e32 v0, v18, v0
	ds_bpermute_b32 v1, v250, v0
	s_and_saveexec_b64 s[0:1], s[8:9]
	s_cbranch_execz .LBB0_780
	s_waitcnt lgkmcnt(0)
	v_add_f32_e32 v0, v0, v1
	v_fma_f32 v0, v0, s6, 0.5
	v_trunc_f32_e32 v0, v0
	v_mul_f32_e32 v1, 0x2f800000, v0
	v_floor_f32_e32 v1, v1
	v_fmac_f32_e32 v0, 0xcf800000, v1
	v_cvt_u32_f32_e32 v0, v0
	v_cvt_u32_f32_e32 v1, v1
	global_atomic_add_x2 v[112:113], v[0:1], off offset:1408

.LBB0_1067:
	s_or_b64 exec, exec, s[2:3]
	v_lshlrev_b32_e32 v96, 16, v172
	s_waitcnt lgkmcnt(0)
	v_and_b32_e32 v97, 0xffff0000, v172
	v_pk_add_f32 v[84:85], v[84:85], v[96:97]
	v_lshlrev_b32_e32 v96, 16, v173
	v_and_b32_e32 v97, 0xffff0000, v173
	v_pk_add_f32 v[86:87], v[86:87], v[96:97]
	v_cvt_pk_bf16_f32 v84, v84, v85
	v_cvt_pk_bf16_f32 v85, v86, v87
	v_lshlrev_b32_e32 v86, 16, v174
	v_and_b32_e32 v87, 0xffff0000, v174
	v_pk_add_f32 v[80:81], v[80:81], v[86:87]
	s_nop 0
	v_cvt_pk_bf16_f32 v86, v80, v81
	v_lshlrev_b32_e32 v80, 16, v175
	v_and_b32_e32 v81, 0xffff0000, v175
	v_pk_add_f32 v[80:81], v[82:83], v[80:81]
	v_lshlrev_b32_e32 v82, 16, v85
	v_cvt_pk_bf16_f32 v87, v80, v81
	v_and_b32_e32 v81, 0xffff0000, v84
	v_lshlrev_b32_e32 v80, 16, v84
	v_mul_f32_e32 v100, v81, v81
	v_fmac_f32_e32 v100, v80, v80
	v_lshlrev_b32_e32 v80, 16, v168
	v_and_b32_e32 v81, 0xffff0000, v168
	v_pk_add_f32 v[80:81], v[92:93], v[80:81]
	v_and_b32_e32 v83, 0xffff0000, v85
	v_cvt_pk_bf16_f32 v92, v80, v81
	v_lshlrev_b32_e32 v80, 16, v169
	v_and_b32_e32 v81, 0xffff0000, v169
	v_fmac_f32_e32 v100, v82, v82
	v_pk_add_f32 v[80:81], v[94:95], v[80:81]
	v_lshlrev_b32_e32 v96, 16, v86
	v_fmac_f32_e32 v100, v83, v83
	v_cvt_pk_bf16_f32 v93, v80, v81
	v_lshlrev_b32_e32 v80, 16, v170
	v_and_b32_e32 v81, 0xffff0000, v170
	v_and_b32_e32 v97, 0xffff0000, v86
	v_fmac_f32_e32 v100, v96, v96
	v_pk_add_f32 v[80:81], v[88:89], v[80:81]
	v_lshlrev_b32_e32 v98, 16, v87
	v_fmac_f32_e32 v100, v97, v97
	v_cvt_pk_bf16_f32 v94, v80, v81
	v_lshlrev_b32_e32 v80, 16, v171
	v_and_b32_e32 v81, 0xffff0000, v171
	v_and_b32_e32 v99, 0xffff0000, v87
	v_fmac_f32_e32 v100, v98, v98
	v_pk_add_f32 v[80:81], v[90:91], v[80:81]
	v_fmac_f32_e32 v100, v99, v99
	v_cvt_pk_bf16_f32 v95, v80, v81
	v_lshlrev_b32_e32 v80, 16, v92
	v_and_b32_e32 v81, 0xffff0000, v92
	v_fmac_f32_e32 v100, v80, v80
	v_lshlrev_b32_e32 v82, 16, v93
	v_fmac_f32_e32 v100, v81, v81
	v_and_b32_e32 v83, 0xffff0000, v93
	v_fmac_f32_e32 v100, v82, v82
	v_lshlrev_b32_e32 v88, 16, v94
	v_fmac_f32_e32 v100, v83, v83
	v_and_b32_e32 v89, 0xffff0000, v94
	v_fmac_f32_e32 v100, v88, v88
	v_lshlrev_b32_e32 v90, 16, v95
	v_fmac_f32_e32 v100, v89, v89
	v_and_b32_e32 v91, 0xffff0000, v95
	v_fmac_f32_e32 v100, v90, v90
	v_fmac_f32_e32 v100, v91, v91
	ds_bpermute_b32 v80, v249, v100
	v_lshl_add_u64 v[82:83], s[10:11], 0, v[228:229]
	v_lshl_add_u64 v[82:83], v[216:217], 1, v[82:83]
	v_mbcnt_lo_u32_b32 v168, -1, 0
	v_mbcnt_hi_u32_b32 v168, -1, v168
	v_and_b32_e32 v169, 15, v168
	v_lshrrev_b32_e32 v170, 4, v168
	v_lshrrev_b32_e32 v182, 2, v169
	v_xor_b32_e32 v182, v182, v170
	v_lshlrev_b32_e32 v182, 4, v182
	v_lshl_or_b32 v182, v169, 6, v182
	s_lshl_b32 s100, s89, 11
	s_add_i32 s100, s100, 0x20000
	v_add_u32_e32 v182, s100, v182
	v_lshl_add_u32 v183, v168, 4, s100
	v_lshrrev_b32_e32 v180, 2, v168
	v_sub_u32_e32 v180, v180, v169
	v_mul_i32_i24_e32 v180, 0x800, v180
	v_and_b32_e32 v181, 3, v168
	v_xor_b32_e32 v181, v181, v170
	v_sub_u32_e32 v181, v181, v170
	v_lshlrev_b32_e32 v181, 4, v181
	v_add_u32_e32 v180, v180, v181
	v_ashrrev_i32_e32 v181, 31, v180
	ds_write_b128 v182, v[84:87]
	ds_read_b128 v[168:171], v183
	v_lshl_add_u64 v[176:177], v[82:83], 0, v[180:181]
	ds_write_b128 v182, v[92:95] offset:1024
	ds_read_b128 v[172:175], v183 offset:1024
	v_lshl_add_u64 v[178:179], v[82:83], 0, v[180:181]
	s_waitcnt lgkmcnt(2)
	global_store_dwordx4 v[176:177], v[168:171], off
	s_waitcnt lgkmcnt(0)
	v_add_f32_e32 v80, v100, v80
	ds_bpermute_b32 v81, v250, v80
	s_and_saveexec_b64 s[2:3], s[6:7]
	s_cbranch_execz .LBB0_1069
	s_waitcnt lgkmcnt(0)
	v_add_f32_e32 v80, v80, v81
	v_fma_f32 v80, v80, s18, 0.5
	v_trunc_f32_e32 v80, v80
	v_mul_f32_e32 v81, 0x2f800000, v80
	v_floor_f32_e32 v81, v81
	v_fmac_f32_e32 v80, 0xcf800000, v81
	v_cvt_u32_f32_e32 v80, v80
	v_cvt_u32_f32_e32 v81, v81
	global_atomic_add_x2 v[112:113], v[80:81], off offset:256
.LBB0_1069:
	s_or_b64 exec, exec, s[2:3]
	v_lshlrev_b32_e32 v80, 16, v164
	s_waitcnt lgkmcnt(0)
	v_and_b32_e32 v81, 0xffff0000, v164
	v_pk_add_f32 v[68:69], v[68:69], v[80:81]
	v_lshlrev_b32_e32 v80, 16, v165
	v_and_b32_e32 v81, 0xffff0000, v165
	v_pk_add_f32 v[70:71], v[70:71], v[80:81]
	v_cvt_pk_bf16_f32 v68, v68, v69
	v_cvt_pk_bf16_f32 v69, v70, v71
	v_lshlrev_b32_e32 v70, 16, v166
	v_and_b32_e32 v71, 0xffff0000, v166
	v_pk_add_f32 v[60:61], v[60:61], v[70:71]
	s_nop 0
	v_cvt_pk_bf16_f32 v70, v60, v61
	v_lshlrev_b32_e32 v60, 16, v167
	v_and_b32_e32 v61, 0xffff0000, v167
	v_pk_add_f32 v[60:61], v[62:63], v[60:61]
	v_lshlrev_b32_e32 v62, 16, v69
	v_cvt_pk_bf16_f32 v71, v60, v61
	v_and_b32_e32 v61, 0xffff0000, v68
	v_lshlrev_b32_e32 v60, 16, v68
	v_mul_f32_e32 v84, v61, v61
	v_fmac_f32_e32 v84, v60, v60
	v_lshlrev_b32_e32 v60, 16, v160
	v_and_b32_e32 v61, 0xffff0000, v160
	v_pk_add_f32 v[60:61], v[76:77], v[60:61]
	v_and_b32_e32 v63, 0xffff0000, v69
	v_cvt_pk_bf16_f32 v76, v60, v61
	v_lshlrev_b32_e32 v60, 16, v161
	v_and_b32_e32 v61, 0xffff0000, v161
	v_fmac_f32_e32 v84, v62, v62
	v_pk_add_f32 v[60:61], v[78:79], v[60:61]
	v_lshlrev_b32_e32 v80, 16, v70
	v_fmac_f32_e32 v84, v63, v63
	v_cvt_pk_bf16_f32 v77, v60, v61
	v_lshlrev_b32_e32 v60, 16, v162
	v_and_b32_e32 v61, 0xffff0000, v162
	v_and_b32_e32 v81, 0xffff0000, v70
	v_fmac_f32_e32 v84, v80, v80
	v_pk_add_f32 v[60:61], v[72:73], v[60:61]
	v_lshlrev_b32_e32 v82, 16, v71
	v_fmac_f32_e32 v84, v81, v81
	v_cvt_pk_bf16_f32 v78, v60, v61
	v_lshlrev_b32_e32 v60, 16, v163
	v_and_b32_e32 v61, 0xffff0000, v163
	v_and_b32_e32 v83, 0xffff0000, v71
	v_fmac_f32_e32 v84, v82, v82
	v_pk_add_f32 v[60:61], v[74:75], v[60:61]
	v_fmac_f32_e32 v84, v83, v83
	v_cvt_pk_bf16_f32 v79, v60, v61
	v_lshlrev_b32_e32 v60, 16, v76
	v_and_b32_e32 v61, 0xffff0000, v76
	v_fmac_f32_e32 v84, v60, v60
	v_lshlrev_b32_e32 v62, 16, v77
	v_fmac_f32_e32 v84, v61, v61
	v_and_b32_e32 v63, 0xffff0000, v77
	v_fmac_f32_e32 v84, v62, v62
	v_lshlrev_b32_e32 v72, 16, v78
	v_fmac_f32_e32 v84, v63, v63
	v_and_b32_e32 v73, 0xffff0000, v78
	v_fmac_f32_e32 v84, v72, v72
	v_lshlrev_b32_e32 v74, 16, v79
	v_fmac_f32_e32 v84, v73, v73
	v_and_b32_e32 v75, 0xffff0000, v79
	v_fmac_f32_e32 v84, v74, v74
	v_fmac_f32_e32 v84, v75, v75
	ds_bpermute_b32 v60, v249, v84
	v_lshl_add_u64 v[62:63], s[10:11], 0, v[226:227]
	v_lshl_add_u64 v[62:63], v[216:217], 1, v[62:63]
	ds_write_b128 v182, v[68:71]
	ds_read_b128 v[168:171], v183
	v_lshl_add_u64 v[176:177], v[62:63], 0, v[180:181]
	s_waitcnt lgkmcnt(2)
	global_store_dwordx4 v[178:179], v[172:175], off offset:256
	ds_write_b128 v182, v[76:79] offset:1024
	ds_read_b128 v[172:175], v183 offset:1024
	v_lshl_add_u64 v[178:179], v[62:63], 0, v[180:181]
	s_waitcnt lgkmcnt(2)
	global_store_dwordx4 v[176:177], v[168:171], off
	s_waitcnt lgkmcnt(0)
	v_add_f32_e32 v60, v84, v60
	ds_bpermute_b32 v61, v250, v60
	s_and_saveexec_b64 s[2:3], s[6:7]
	s_mov_b32 s20, 0x800000
	s_cbranch_execz .LBB0_1071
	s_waitcnt lgkmcnt(0)
	v_add_f32_e32 v60, v60, v61
	v_fma_f32 v60, v60, s18, 0.5
	v_trunc_f32_e32 v60, v60
	v_mul_f32_e32 v61, 0x2f800000, v60
	v_floor_f32_e32 v61, v61
	v_fmac_f32_e32 v60, 0xcf800000, v61
	v_cvt_u32_f32_e32 v60, v60
	v_cvt_u32_f32_e32 v61, v61
	global_atomic_add_x2 v[112:113], v[60:61], off offset:384
.LBB0_1071:
	s_or_b64 exec, exec, s[2:3]
	v_lshlrev_b32_e32 v60, 16, v156
	s_waitcnt lgkmcnt(0)
	v_and_b32_e32 v61, 0xffff0000, v156
	v_pk_add_f32 v[52:53], v[52:53], v[60:61]
	v_lshlrev_b32_e32 v60, 16, v157
	v_and_b32_e32 v61, 0xffff0000, v157
	v_pk_add_f32 v[54:55], v[54:55], v[60:61]
	v_cvt_pk_bf16_f32 v52, v52, v53
	v_cvt_pk_bf16_f32 v53, v54, v55
	v_lshlrev_b32_e32 v54, 16, v158
	v_and_b32_e32 v55, 0xffff0000, v158
	v_pk_add_f32 v[48:49], v[48:49], v[54:55]
	s_nop 0
	v_cvt_pk_bf16_f32 v54, v48, v49
	v_lshlrev_b32_e32 v48, 16, v159
	v_and_b32_e32 v49, 0xffff0000, v159
	v_pk_add_f32 v[48:49], v[50:51], v[48:49]
	v_lshlrev_b32_e32 v50, 16, v53
	v_cvt_pk_bf16_f32 v55, v48, v49
	v_and_b32_e32 v49, 0xffff0000, v52
	v_lshlrev_b32_e32 v48, 16, v52
	v_mul_f32_e32 v68, v49, v49
	v_fmac_f32_e32 v68, v48, v48
	v_and_b32_e32 v51, 0xffff0000, v53
	v_fmac_f32_e32 v68, v50, v50
	v_lshlrev_b32_e32 v48, 16, v152
	v_and_b32_e32 v49, 0xffff0000, v152
	v_lshlrev_b32_e32 v60, 16, v54
	v_fmac_f32_e32 v68, v51, v51
	v_pk_add_f32 v[48:49], v[64:65], v[48:49]
	v_fmac_f32_e32 v68, v60, v60
	v_cvt_pk_bf16_f32 v60, v48, v49
	v_lshlrev_b32_e32 v48, 16, v153
	v_and_b32_e32 v49, 0xffff0000, v153
	v_and_b32_e32 v61, 0xffff0000, v54
	v_pk_add_f32 v[48:49], v[66:67], v[48:49]
	v_fmac_f32_e32 v68, v61, v61
	v_cvt_pk_bf16_f32 v61, v48, v49
	v_lshlrev_b32_e32 v48, 16, v154
	v_and_b32_e32 v49, 0xffff0000, v154
	v_lshlrev_b32_e32 v62, 16, v55
	v_pk_add_f32 v[48:49], v[56:57], v[48:49]
	v_fmac_f32_e32 v68, v62, v62
	v_cvt_pk_bf16_f32 v62, v48, v49
	v_lshlrev_b32_e32 v48, 16, v155
	v_and_b32_e32 v49, 0xffff0000, v155
	v_and_b32_e32 v63, 0xffff0000, v55
	v_pk_add_f32 v[48:49], v[58:59], v[48:49]
	v_fmac_f32_e32 v68, v63, v63
	v_cvt_pk_bf16_f32 v63, v48, v49
	v_lshlrev_b32_e32 v48, 16, v60
	v_and_b32_e32 v49, 0xffff0000, v60
	v_fmac_f32_e32 v68, v48, v48
	v_lshlrev_b32_e32 v50, 16, v61
	v_fmac_f32_e32 v68, v49, v49
	v_and_b32_e32 v51, 0xffff0000, v61
	v_fmac_f32_e32 v68, v50, v50
	v_lshlrev_b32_e32 v56, 16, v62
	v_fmac_f32_e32 v68, v51, v51
	v_and_b32_e32 v57, 0xffff0000, v62
	v_fmac_f32_e32 v68, v56, v56
	v_lshlrev_b32_e32 v58, 16, v63
	v_fmac_f32_e32 v68, v57, v57
	v_and_b32_e32 v59, 0xffff0000, v63
	v_fmac_f32_e32 v68, v58, v58
	v_fmac_f32_e32 v68, v59, v59
	ds_bpermute_b32 v48, v249, v68
	v_lshl_add_u64 v[50:51], s[10:11], 0, v[224:225]
	v_lshl_add_u64 v[50:51], v[216:217], 1, v[50:51]
	ds_write_b128 v182, v[52:55]
	ds_read_b128 v[168:171], v183
	v_lshl_add_u64 v[176:177], v[50:51], 0, v[180:181]
	s_waitcnt lgkmcnt(2)
	global_store_dwordx4 v[178:179], v[172:175], off offset:256
	ds_write_b128 v182, v[60:63] offset:1024
	ds_read_b128 v[172:175], v183 offset:1024
	v_lshl_add_u64 v[178:179], v[50:51], 0, v[180:181]
	s_waitcnt lgkmcnt(2)
	global_store_dwordx4 v[176:177], v[168:171], off
	s_waitcnt lgkmcnt(0)
	v_add_f32_e32 v48, v68, v48
	ds_bpermute_b32 v49, v250, v48
	s_and_saveexec_b64 s[2:3], s[6:7]
	s_cbranch_execz .LBB0_1073
	s_waitcnt lgkmcnt(0)
	v_add_f32_e32 v48, v48, v49
	v_fma_f32 v48, v48, s18, 0.5
	v_trunc_f32_e32 v48, v48
	v_mul_f32_e32 v49, 0x2f800000, v48
	v_floor_f32_e32 v49, v49
	v_fmac_f32_e32 v48, 0xcf800000, v49
	v_cvt_u32_f32_e32 v48, v48
	v_cvt_u32_f32_e32 v49, v49
	global_atomic_add_x2 v[112:113], v[48:49], off offset:1024
.LBB0_1073:
	s_or_b64 exec, exec, s[2:3]
	v_lshlrev_b32_e32 v48, 16, v148
	s_waitcnt lgkmcnt(0)
	v_and_b32_e32 v49, 0xffff0000, v148
	v_pk_add_f32 v[36:37], v[36:37], v[48:49]
	v_lshlrev_b32_e32 v48, 16, v149
	v_and_b32_e32 v49, 0xffff0000, v149
	v_pk_add_f32 v[38:39], v[38:39], v[48:49]
	v_cvt_pk_bf16_f32 v36, v36, v37
	v_cvt_pk_bf16_f32 v37, v38, v39
	v_lshlrev_b32_e32 v38, 16, v150
	v_and_b32_e32 v39, 0xffff0000, v150
	v_pk_add_f32 v[32:33], v[32:33], v[38:39]
	s_nop 0
	v_cvt_pk_bf16_f32 v38, v32, v33
	v_lshlrev_b32_e32 v32, 16, v151
	v_and_b32_e32 v33, 0xffff0000, v151
	v_pk_add_f32 v[32:33], v[34:35], v[32:33]
	v_lshlrev_b32_e32 v34, 16, v37
	v_cvt_pk_bf16_f32 v39, v32, v33
	v_and_b32_e32 v33, 0xffff0000, v36
	v_lshlrev_b32_e32 v32, 16, v36
	v_mul_f32_e32 v52, v33, v33
	v_fmac_f32_e32 v52, v32, v32
	v_lshlrev_b32_e32 v32, 16, v144
	v_and_b32_e32 v33, 0xffff0000, v144
	v_pk_add_f32 v[32:33], v[44:45], v[32:33]
	v_and_b32_e32 v35, 0xffff0000, v37
	v_cvt_pk_bf16_f32 v44, v32, v33
	v_lshlrev_b32_e32 v32, 16, v145
	v_and_b32_e32 v33, 0xffff0000, v145
	v_fmac_f32_e32 v52, v34, v34
	v_pk_add_f32 v[32:33], v[46:47], v[32:33]
	v_lshlrev_b32_e32 v48, 16, v38
	v_fmac_f32_e32 v52, v35, v35
	v_cvt_pk_bf16_f32 v45, v32, v33
	v_lshlrev_b32_e32 v32, 16, v146
	v_and_b32_e32 v33, 0xffff0000, v146
	v_and_b32_e32 v49, 0xffff0000, v38
	v_fmac_f32_e32 v52, v48, v48
	v_pk_add_f32 v[32:33], v[40:41], v[32:33]
	v_lshlrev_b32_e32 v50, 16, v39
	v_fmac_f32_e32 v52, v49, v49
	v_cvt_pk_bf16_f32 v46, v32, v33
	v_lshlrev_b32_e32 v32, 16, v147
	v_and_b32_e32 v33, 0xffff0000, v147
	v_and_b32_e32 v51, 0xffff0000, v39
	v_fmac_f32_e32 v52, v50, v50
	v_pk_add_f32 v[32:33], v[42:43], v[32:33]
	v_fmac_f32_e32 v52, v51, v51
	v_cvt_pk_bf16_f32 v47, v32, v33
	v_lshlrev_b32_e32 v32, 16, v44
	v_and_b32_e32 v33, 0xffff0000, v44
	v_fmac_f32_e32 v52, v32, v32
	v_lshlrev_b32_e32 v34, 16, v45
	v_fmac_f32_e32 v52, v33, v33
	v_and_b32_e32 v35, 0xffff0000, v45
	v_fmac_f32_e32 v52, v34, v34
	v_lshlrev_b32_e32 v40, 16, v46
	v_fmac_f32_e32 v52, v35, v35
	v_and_b32_e32 v41, 0xffff0000, v46
	v_fmac_f32_e32 v52, v40, v40
	v_lshlrev_b32_e32 v42, 16, v47
	v_fmac_f32_e32 v52, v41, v41
	v_and_b32_e32 v43, 0xffff0000, v47
	v_fmac_f32_e32 v52, v42, v42
	v_fmac_f32_e32 v52, v43, v43
	ds_bpermute_b32 v32, v249, v52
	v_lshl_add_u64 v[34:35], s[10:11], 0, v[222:223]
	v_lshl_add_u64 v[34:35], v[216:217], 1, v[34:35]
	ds_write_b128 v182, v[36:39]
	ds_read_b128 v[168:171], v183
	v_lshl_add_u64 v[176:177], v[34:35], 0, v[180:181]
	s_waitcnt lgkmcnt(2)
	global_store_dwordx4 v[178:179], v[172:175], off offset:256
	ds_write_b128 v182, v[44:47] offset:1024
	ds_read_b128 v[172:175], v183 offset:1024
	v_lshl_add_u64 v[178:179], v[34:35], 0, v[180:181]
	s_waitcnt lgkmcnt(2)
	global_store_dwordx4 v[176:177], v[168:171], off
	s_waitcnt lgkmcnt(0)
	v_add_f32_e32 v32, v52, v32
	ds_bpermute_b32 v33, v250, v32
	s_and_saveexec_b64 s[2:3], s[6:7]
	s_cbranch_execz .LBB0_1075
	s_waitcnt lgkmcnt(0)
	v_add_f32_e32 v32, v32, v33
	v_fma_f32 v32, v32, s18, 0.5
	v_trunc_f32_e32 v32, v32
	v_mul_f32_e32 v33, 0x2f800000, v32
	v_floor_f32_e32 v33, v33
	v_fmac_f32_e32 v32, 0xcf800000, v33
	v_cvt_u32_f32_e32 v32, v32
	v_cvt_u32_f32_e32 v33, v33
	global_atomic_add_x2 v[112:113], v[32:33], off offset:1152
.LBB0_1075:
	s_or_b64 exec, exec, s[2:3]
	v_lshlrev_b32_e32 v32, 16, v140
	s_waitcnt lgkmcnt(0)
	v_and_b32_e32 v33, 0xffff0000, v140
	v_pk_add_f32 v[20:21], v[20:21], v[32:33]
	v_lshlrev_b32_e32 v32, 16, v141
	v_and_b32_e32 v33, 0xffff0000, v141
	v_pk_add_f32 v[22:23], v[22:23], v[32:33]
	v_cvt_pk_bf16_f32 v20, v20, v21
	v_cvt_pk_bf16_f32 v21, v22, v23
	v_lshlrev_b32_e32 v22, 16, v142
	v_and_b32_e32 v23, 0xffff0000, v142
	v_pk_add_f32 v[16:17], v[16:17], v[22:23]
	s_nop 0
	v_cvt_pk_bf16_f32 v22, v16, v17
	v_lshlrev_b32_e32 v16, 16, v143
	v_and_b32_e32 v17, 0xffff0000, v143
	v_pk_add_f32 v[16:17], v[18:19], v[16:17]
	v_lshlrev_b32_e32 v18, 16, v21
	v_cvt_pk_bf16_f32 v23, v16, v17
	v_and_b32_e32 v17, 0xffff0000, v20
	v_lshlrev_b32_e32 v16, 16, v20
	v_mul_f32_e32 v36, v17, v17
	v_fmac_f32_e32 v36, v16, v16
	v_lshlrev_b32_e32 v16, 16, v136
	v_and_b32_e32 v17, 0xffff0000, v136
	v_pk_add_f32 v[16:17], v[28:29], v[16:17]
	v_and_b32_e32 v19, 0xffff0000, v21
	v_cvt_pk_bf16_f32 v28, v16, v17
	v_lshlrev_b32_e32 v16, 16, v137
	v_and_b32_e32 v17, 0xffff0000, v137
	v_fmac_f32_e32 v36, v18, v18
	v_pk_add_f32 v[16:17], v[30:31], v[16:17]
	v_lshlrev_b32_e32 v32, 16, v22
	v_fmac_f32_e32 v36, v19, v19
	v_cvt_pk_bf16_f32 v29, v16, v17
	v_lshlrev_b32_e32 v16, 16, v138
	v_and_b32_e32 v17, 0xffff0000, v138
	v_and_b32_e32 v33, 0xffff0000, v22
	v_fmac_f32_e32 v36, v32, v32
	v_pk_add_f32 v[16:17], v[24:25], v[16:17]
	v_lshlrev_b32_e32 v34, 16, v23
	v_fmac_f32_e32 v36, v33, v33
	v_cvt_pk_bf16_f32 v30, v16, v17
	v_lshlrev_b32_e32 v16, 16, v139
	v_and_b32_e32 v17, 0xffff0000, v139
	v_and_b32_e32 v35, 0xffff0000, v23
	v_fmac_f32_e32 v36, v34, v34
	v_pk_add_f32 v[16:17], v[26:27], v[16:17]
	v_fmac_f32_e32 v36, v35, v35
	v_cvt_pk_bf16_f32 v31, v16, v17
	v_lshlrev_b32_e32 v16, 16, v28
	v_and_b32_e32 v17, 0xffff0000, v28
	v_fmac_f32_e32 v36, v16, v16
	v_lshlrev_b32_e32 v18, 16, v29
	v_fmac_f32_e32 v36, v17, v17
	v_and_b32_e32 v19, 0xffff0000, v29
	v_fmac_f32_e32 v36, v18, v18
	v_lshlrev_b32_e32 v24, 16, v30
	v_fmac_f32_e32 v36, v19, v19
	v_and_b32_e32 v25, 0xffff0000, v30
	v_fmac_f32_e32 v36, v24, v24
	v_lshlrev_b32_e32 v26, 16, v31
	v_fmac_f32_e32 v36, v25, v25
	v_and_b32_e32 v27, 0xffff0000, v31
	v_fmac_f32_e32 v36, v26, v26
	v_fmac_f32_e32 v36, v27, v27
	ds_bpermute_b32 v16, v249, v36
	v_lshl_add_u64 v[18:19], s[10:11], 0, v[220:221]
	v_lshl_add_u64 v[18:19], v[216:217], 1, v[18:19]
	ds_write_b128 v182, v[20:23]
	ds_read_b128 v[168:171], v183
	v_lshl_add_u64 v[176:177], v[18:19], 0, v[180:181]
	s_waitcnt lgkmcnt(2)
	global_store_dwordx4 v[178:179], v[172:175], off offset:256
	ds_write_b128 v182, v[28:31] offset:1024
	ds_read_b128 v[172:175], v183 offset:1024
	v_lshl_add_u64 v[178:179], v[18:19], 0, v[180:181]
	s_waitcnt lgkmcnt(2)
	global_store_dwordx4 v[176:177], v[168:171], off
	s_waitcnt lgkmcnt(0)
	v_add_f32_e32 v16, v36, v16
	ds_bpermute_b32 v17, v250, v16
	s_and_saveexec_b64 s[2:3], s[6:7]
	s_cbranch_execz .LBB0_1077
	s_waitcnt lgkmcnt(0)
	v_add_f32_e32 v16, v16, v17
	v_fma_f32 v16, v16, s18, 0.5
	v_trunc_f32_e32 v16, v16
	v_mul_f32_e32 v17, 0x2f800000, v16
	v_floor_f32_e32 v17, v17
	v_fmac_f32_e32 v16, 0xcf800000, v17
	v_cvt_u32_f32_e32 v16, v16
	v_cvt_u32_f32_e32 v17, v17
	global_atomic_add_x2 v[112:113], v[16:17], off offset:1280
.LBB0_1077:
	s_or_b64 exec, exec, s[2:3]
	v_lshlrev_b32_e32 v18, 16, v132
	v_and_b32_e32 v19, 0xffff0000, v132
	v_pk_add_f32 v[4:5], v[4:5], v[18:19]
	v_lshlrev_b32_e32 v18, 16, v133
	v_and_b32_e32 v19, 0xffff0000, v133
	v_pk_add_f32 v[6:7], v[6:7], v[18:19]
	v_cvt_pk_bf16_f32 v4, v4, v5
	v_cvt_pk_bf16_f32 v5, v6, v7
	v_lshlrev_b32_e32 v6, 16, v134
	v_and_b32_e32 v7, 0xffff0000, v134
	v_pk_add_f32 v[0:1], v[0:1], v[6:7]
	s_waitcnt lgkmcnt(0)
	v_lshl_add_u64 v[16:17], s[10:11], 0, v[218:219]
	v_cvt_pk_bf16_f32 v6, v0, v1
	v_lshlrev_b32_e32 v0, 16, v135
	v_and_b32_e32 v1, 0xffff0000, v135
	v_pk_add_f32 v[0:1], v[2:3], v[0:1]
	v_lshlrev_b32_e32 v2, 16, v5
	v_cvt_pk_bf16_f32 v7, v0, v1
	v_and_b32_e32 v1, 0xffff0000, v4
	v_lshlrev_b32_e32 v0, 16, v4
	v_mul_f32_e32 v18, v1, v1
	v_fmac_f32_e32 v18, v0, v0
	v_lshl_add_u64 v[16:17], v[216:217], 1, v[16:17]
	v_and_b32_e32 v3, 0xffff0000, v5
	v_fmac_f32_e32 v18, v2, v2
	ds_write_b128 v182, v[4:7]
	ds_read_b128 v[168:171], v183
	v_lshl_add_u64 v[176:177], v[16:17], 0, v[180:181]
	s_waitcnt lgkmcnt(2)
	global_store_dwordx4 v[178:179], v[172:175], off offset:256
	v_fmac_f32_e32 v18, v3, v3
	v_lshlrev_b32_e32 v0, 16, v128
	v_lshlrev_b32_e32 v4, 16, v6
	v_and_b32_e32 v1, 0xffff0000, v128
	v_lshlrev_b32_e32 v2, 16, v129
	v_and_b32_e32 v3, 0xffff0000, v129
	v_and_b32_e32 v5, 0xffff0000, v6
	v_fmac_f32_e32 v18, v4, v4
	v_pk_add_f32 v[0:1], v[12:13], v[0:1]
	v_pk_add_f32 v[2:3], v[14:15], v[2:3]
	v_lshlrev_b32_e32 v6, 16, v7
	v_fmac_f32_e32 v18, v5, v5
	v_cvt_pk_bf16_f32 v0, v0, v1
	v_cvt_pk_bf16_f32 v1, v2, v3
	v_lshlrev_b32_e32 v2, 16, v130
	v_and_b32_e32 v3, 0xffff0000, v130
	v_lshlrev_b32_e32 v4, 16, v131
	v_and_b32_e32 v5, 0xffff0000, v131
	v_and_b32_e32 v7, 0xffff0000, v7
	v_fmac_f32_e32 v18, v6, v6
	v_pk_add_f32 v[2:3], v[8:9], v[2:3]
	v_pk_add_f32 v[4:5], v[10:11], v[4:5]
	v_fmac_f32_e32 v18, v7, v7
	v_cvt_pk_bf16_f32 v2, v2, v3
	v_cvt_pk_bf16_f32 v3, v4, v5
	v_lshlrev_b32_e32 v4, 16, v0
	ds_write_b128 v182, v[0:3] offset:1024
	ds_read_b128 v[172:175], v183 offset:1024
	v_lshl_add_u64 v[178:179], v[16:17], 0, v[180:181]
	s_waitcnt lgkmcnt(2)
	global_store_dwordx4 v[176:177], v[168:171], off
	s_waitcnt lgkmcnt(0)
	global_store_dwordx4 v[178:179], v[172:175], off offset:256
	v_fmac_f32_e32 v18, v4, v4
	v_lshlrev_b32_e32 v5, 16, v1
	v_and_b32_e32 v0, 0xffff0000, v0
	v_fmac_f32_e32 v18, v0, v0
	v_and_b32_e32 v1, 0xffff0000, v1
	v_fmac_f32_e32 v18, v5, v5
	v_lshlrev_b32_e32 v6, 16, v2
	v_fmac_f32_e32 v18, v1, v1
	v_and_b32_e32 v2, 0xffff0000, v2
	v_fmac_f32_e32 v18, v6, v6
	v_lshlrev_b32_e32 v7, 16, v3
	v_fmac_f32_e32 v18, v2, v2
	v_and_b32_e32 v3, 0xffff0000, v3
	v_fmac_f32_e32 v18, v7, v7
	v_fmac_f32_e32 v18, v3, v3
	ds_bpermute_b32 v0, v249, v18
	s_waitcnt lgkmcnt(0)
	v_add_f32_e32 v0, v18, v0
	ds_bpermute_b32 v1, v250, v0
	s_and_saveexec_b64 s[2:3], s[6:7]
	s_cbranch_execz .LBB0_1079
	s_waitcnt lgkmcnt(0)
	v_add_f32_e32 v0, v0, v1
	v_fma_f32 v0, v0, s18, 0.5
	v_trunc_f32_e32 v0, v0
	v_mul_f32_e32 v1, 0x2f800000, v0
	v_floor_f32_e32 v1, v1
	v_fmac_f32_e32 v0, 0xcf800000, v1
	v_cvt_u32_f32_e32 v0, v0
	v_cvt_u32_f32_e32 v1, v1
	global_atomic_add_x2 v[112:113], v[0:1], off offset:1408
